# GQA NOMAX tile loop: LDS fragment reads fed through the QK MFMA gaps with counted lgkmcnt instead of one 24-read burst in front of the first MFMA
# speedup vs baseline: 1.0012x; 1.0012x over previous
.LBB0_580:
	ds_read_b128 v[32:35], v194
	ds_read_b128 v[36:39], v194 offset:4608
	ds_read_b128 v[96:99], v194 offset:32
	ds_read_b128 v[104:107], v194 offset:4640
	s_waitcnt lgkmcnt(3)
	v_mfma_f32_32x32x16_bf16 v[48:63], v[32:35], v[64:67], 0
	s_add_i32 s15, s14, 1
	s_cmp_ge_u32 s15, s37
	ds_read_b128 v[114:117], v194 offset:64
	s_waitcnt lgkmcnt(3)
	v_mfma_f32_32x32x16_bf16 v[32:47], v[36:39], v[64:67], 0
	ds_read_b128 v[122:125], v194 offset:4672
	s_waitcnt lgkmcnt(3)
	v_mfma_f32_32x32x16_bf16 v[48:63], v[96:99], v[68:71], v[48:63]
	ds_read_b128 v[118:121], v194 offset:96
	s_waitcnt lgkmcnt(3)
	v_mfma_f32_32x32x16_bf16 v[32:47], v[104:107], v[68:71], v[32:47]
	ds_read_b128 v[134:137], v194 offset:4704
	s_waitcnt lgkmcnt(3)
	v_mfma_f32_32x32x16_bf16 v[48:63], v[114:117], v[72:75], v[48:63]
	ds_read_b64_tr_b16 v[138:139], v218 offset:9216
	ds_read_b64_tr_b16 v[140:141], v218 offset:10240
	s_waitcnt lgkmcnt(4)
	v_mfma_f32_32x32x16_bf16 v[32:47], v[122:125], v[72:75], v[32:47]
	ds_read_b64_tr_b16 v[148:149], v218 offset:10496
	ds_read_b64_tr_b16 v[146:147], v218 offset:9472
	s_waitcnt lgkmcnt(5)
	v_mfma_f32_32x32x16_bf16 v[48:63], v[118:121], v[76:79], v[48:63]
	ds_read_b64_tr_b16 v[152:153], v218 offset:11264
	ds_read_b64_tr_b16 v[154:155], v218 offset:12288
	s_waitcnt lgkmcnt(6)
	v_mfma_f32_32x32x16_bf16 v[32:47], v[134:137], v[76:79], v[32:47]
	ds_read_b64_tr_b16 v[158:159], v218 offset:12544
	ds_read_b64_tr_b16 v[156:157], v218 offset:11520
	ds_read_b64_tr_b16 v[160:161], v218 offset:13312
	ds_read_b64_tr_b16 v[162:163], v218 offset:14336
	ds_read_b64_tr_b16 v[166:167], v218 offset:14592
	ds_read_b64_tr_b16 v[164:165], v218 offset:13568
	ds_read_b64_tr_b16 v[168:169], v218 offset:15360
	ds_read_b64_tr_b16 v[170:171], v218 offset:16384
	ds_read_b64_tr_b16 v[174:175], v218 offset:16640
	ds_read_b64_tr_b16 v[172:173], v218 offset:15616
	s_nop 10
	v_exp_f32_e32 v96, v48
	v_exp_f32_e32 v97, v49
	v_exp_f32_e32 v98, v50
	v_exp_f32_e32 v99, v51
	v_exp_f32_e32 v104, v52
	v_exp_f32_e32 v105, v53
	v_exp_f32_e32 v106, v54
	v_exp_f32_e32 v109, v32
	v_exp_f32_e32 v110, v33
	v_exp_f32_e32 v111, v34
	v_exp_f32_e32 v114, v35
	v_exp_f32_e32 v107, v55
	v_cvt_pk_bf16_f32 v32, v96, v97
	v_cvt_pk_bf16_f32 v33, v98, v99
	v_cvt_pk_bf16_f32 v34, v104, v105
	v_cvt_pk_bf16_f32 v35, v106, v107
	v_exp_f32_e32 v115, v36
	s_waitcnt lgkmcnt(14)
	v_mfma_f32_32x32x16_bf16 v[0:15], v[138:141], v[32:35], v[0:15]
	v_exp_f32_e32 v116, v37
	v_exp_f32_e32 v117, v38
	v_exp_f32_e32 v118, v39
	v_exp_f32_e32 v119, v56
	v_exp_f32_e32 v120, v57
	v_exp_f32_e32 v126, v58
	v_exp_f32_e32 v125, v59
	s_waitcnt lgkmcnt(12)
	v_mfma_f32_32x32x16_bf16 v[16:31], v[146:149], v[32:35], v[16:31]
	v_exp_f32_e32 v124, v60
	v_exp_f32_e32 v123, v61
	v_exp_f32_e32 v122, v62
	v_exp_f32_e32 v121, v63
	v_cvt_pk_bf16_f32 v36, v109, v110
	v_cvt_pk_bf16_f32 v37, v111, v114
	v_cvt_pk_bf16_f32 v38, v115, v116
	v_cvt_pk_bf16_f32 v39, v117, v118
	v_cvt_pk_bf16_f32 v32, v119, v120
	v_cvt_pk_bf16_f32 v33, v126, v125
	v_cvt_pk_bf16_f32 v34, v124, v123
	v_cvt_pk_bf16_f32 v35, v122, v121
	v_exp_f32_e32 v138, v40
	s_waitcnt lgkmcnt(10)
	v_mfma_f32_32x32x16_bf16 v[0:15], v[152:155], v[32:35], v[0:15]
	v_exp_f32_e32 v137, v41
	v_exp_f32_e32 v136, v42
	v_exp_f32_e32 v134, v43
	v_exp_f32_e32 v131, v44
	v_exp_f32_e32 v135, v45
	v_exp_f32_e32 v133, v46
	v_exp_f32_e32 v127, v47
	s_waitcnt lgkmcnt(8)
	v_mfma_f32_32x32x16_bf16 v[16:31], v[156:159], v[32:35], v[16:31]
	v_cvt_pk_bf16_f32 v32, v138, v137
	v_cvt_pk_bf16_f32 v33, v136, v134
	v_cvt_pk_bf16_f32 v34, v131, v135
	v_cvt_pk_bf16_f32 v35, v133, v127
	s_waitcnt lgkmcnt(6)
	v_mfma_f32_32x32x16_bf16 v[0:15], v[160:163], v[36:39], v[0:15]
	s_waitcnt lgkmcnt(4)
	v_mfma_f32_32x32x16_bf16 v[16:31], v[164:167], v[36:39], v[16:31]
	s_waitcnt lgkmcnt(2)
	v_mfma_f32_32x32x16_bf16 v[0:15], v[168:171], v[32:35], v[0:15]
	s_waitcnt lgkmcnt(0)
	v_mfma_f32_32x32x16_bf16 v[16:31], v[172:175], v[32:35], v[16:31]
	s_cbranch_scc1 .LBB0_582
	s_cmp_ge_u32 s13, s37
	s_cbranch_scc1 .Lgqa_w0_tail
	s_waitcnt vmcnt(3)
	ds_write_b128 v193, v[88:91] offset:17408
	s_waitcnt vmcnt(2)
	ds_write_b128 v219, v[92:95] offset:26624
	s_branch .LBB0_582

.LBB0_584:
	ds_read_b128 v[32:35], v194 offset:17408
	ds_read_b128 v[36:39], v194 offset:22016
	ds_read_b128 v[140:143], v194 offset:17440
	ds_read_b128 v[146:149], v194 offset:22048
	s_waitcnt lgkmcnt(3)
	v_mfma_f32_32x32x16_bf16 v[48:63], v[32:35], v[64:67], 0
	s_andn2_b64 vcc, exec, s[10:11]
	ds_read_b128 v[152:155], v194 offset:17472
	s_waitcnt lgkmcnt(3)
	v_mfma_f32_32x32x16_bf16 v[32:47], v[36:39], v[64:67], 0
	ds_read_b128 v[160:163], v194 offset:22080
	s_waitcnt lgkmcnt(3)
	v_mfma_f32_32x32x16_bf16 v[48:63], v[140:143], v[68:71], v[48:63]
	ds_read_b128 v[156:159], v194 offset:17504
	s_waitcnt lgkmcnt(3)
	v_mfma_f32_32x32x16_bf16 v[32:47], v[146:149], v[68:71], v[32:47]
	ds_read_b128 v[164:167], v194 offset:22112
	s_waitcnt lgkmcnt(3)
	v_mfma_f32_32x32x16_bf16 v[48:63], v[152:155], v[72:75], v[48:63]
	ds_read_b64_tr_b16 v[168:169], v218 offset:26624
	ds_read_b64_tr_b16 v[170:171], v218 offset:27648
	s_waitcnt lgkmcnt(4)
	v_mfma_f32_32x32x16_bf16 v[32:47], v[160:163], v[72:75], v[32:47]
	ds_read_b64_tr_b16 v[174:175], v218 offset:27904
	ds_read_b64_tr_b16 v[172:173], v218 offset:26880
	s_waitcnt lgkmcnt(5)
	v_mfma_f32_32x32x16_bf16 v[48:63], v[156:159], v[76:79], v[48:63]
	ds_read_b64_tr_b16 v[176:177], v218 offset:28672
	ds_read_b64_tr_b16 v[178:179], v218 offset:29696
	s_waitcnt lgkmcnt(6)
	v_mfma_f32_32x32x16_bf16 v[32:47], v[164:167], v[76:79], v[32:47]
	ds_read_b64_tr_b16 v[182:183], v218 offset:29952
	ds_read_b64_tr_b16 v[180:181], v218 offset:28928
	ds_read_b64_tr_b16 v[184:185], v218 offset:30720
	ds_read_b64_tr_b16 v[186:187], v218 offset:31744
	ds_read_b64_tr_b16 v[190:191], v218 offset:32000
	ds_read_b64_tr_b16 v[188:189], v218 offset:30976
	ds_read_b64_tr_b16 v[196:197], v218 offset:32768
	ds_read_b64_tr_b16 v[198:199], v218 offset:33792
	ds_read_b64_tr_b16 v[202:203], v218 offset:34048
	ds_read_b64_tr_b16 v[200:201], v218 offset:33024
	s_nop 10
	v_exp_f32_e32 v48, v48
	v_exp_f32_e32 v141, v58
	v_exp_f32_e32 v140, v59
	v_exp_f32_e32 v60, v60
	v_exp_f32_e32 v59, v61
	v_exp_f32_e32 v58, v62
	v_exp_f32_e32 v139, v32
	v_exp_f32_e32 v32, v49
	v_exp_f32_e32 v49, v33
	v_exp_f32_e32 v33, v50
	v_exp_f32_e32 v50, v34
	v_exp_f32_e32 v34, v51
	v_exp_f32_e32 v51, v35
	v_exp_f32_e32 v35, v52
	v_exp_f32_e32 v52, v36
	v_exp_f32_e32 v36, v53
	v_exp_f32_e32 v53, v37
	v_exp_f32_e32 v37, v54
	v_exp_f32_e32 v54, v38
	v_exp_f32_e32 v38, v55
	v_cvt_pk_bf16_f32 v146, v48, v32
	v_cvt_pk_bf16_f32 v147, v33, v34
	v_cvt_pk_bf16_f32 v148, v35, v36
	v_cvt_pk_bf16_f32 v149, v37, v38
	v_exp_f32_e32 v39, v39
	s_waitcnt lgkmcnt(14)
	v_mfma_f32_32x32x16_bf16 v[0:15], v[168:171], v[146:149], v[0:15]
	v_exp_f32_e32 v55, v56
	v_exp_f32_e32 v56, v57
	v_exp_f32_e32 v57, v63
	v_cvt_pk_bf16_f32 v152, v139, v49
	v_cvt_pk_bf16_f32 v153, v50, v51
	v_cvt_pk_bf16_f32 v154, v52, v53
	v_cvt_pk_bf16_f32 v155, v54, v39
	s_waitcnt lgkmcnt(12)
	v_mfma_f32_32x32x16_bf16 v[16:31], v[172:175], v[146:149], v[16:31]
	v_cvt_pk_bf16_f32 v146, v55, v56
	v_cvt_pk_bf16_f32 v147, v141, v140
	v_cvt_pk_bf16_f32 v148, v60, v59
	v_cvt_pk_bf16_f32 v149, v58, v57
	v_exp_f32_e32 v63, v40
	v_exp_f32_e32 v62, v41
	v_exp_f32_e32 v61, v42
	s_waitcnt lgkmcnt(10)
	v_mfma_f32_32x32x16_bf16 v[0:15], v[176:179], v[146:149], v[0:15]
	v_exp_f32_e32 v43, v43
	v_exp_f32_e32 v41, v44
	v_exp_f32_e32 v44, v45
	v_exp_f32_e32 v42, v46
	v_exp_f32_e32 v40, v47
	s_waitcnt lgkmcnt(8)
	v_mfma_f32_32x32x16_bf16 v[16:31], v[180:183], v[146:149], v[16:31]
	v_cvt_pk_bf16_f32 v146, v63, v62
	v_cvt_pk_bf16_f32 v147, v61, v43
	v_cvt_pk_bf16_f32 v148, v41, v44
	v_cvt_pk_bf16_f32 v149, v42, v40
	s_waitcnt lgkmcnt(6)
	v_mfma_f32_32x32x16_bf16 v[0:15], v[184:187], v[152:155], v[0:15]
	s_waitcnt lgkmcnt(4)
	v_mfma_f32_32x32x16_bf16 v[16:31], v[188:191], v[152:155], v[16:31]
	s_waitcnt lgkmcnt(2)
	v_mfma_f32_32x32x16_bf16 v[0:15], v[196:199], v[146:149], v[0:15]
	s_waitcnt lgkmcnt(0)
	v_mfma_f32_32x32x16_bf16 v[16:31], v[200:203], v[146:149], v[16:31]
	s_cbranch_vccnz .LBB0_586
	s_cmp_ge_u32 s14, s12
	s_cbranch_scc1 .Lgqa_w1_tail
	s_waitcnt vmcnt(3)
	ds_write_b128 v193, v[80:83]
	s_waitcnt vmcnt(2)
	ds_write_b128 v219, v[84:87] offset:9216
	s_branch .LBB0_586
